# MLA kv step heads: K-fragment ds_reads issued first, next-tile address math and global loads moved behind the first MFMA
# speedup vs baseline: 1.0124x; 1.0005x over previous
.LBB0_733:
	ds_read_b128 v[66:69], v219 offset:13312
	ds_read_b128 v[174:177], v219 offset:13344
	ds_read_b128 v[86:89], v219 offset:19968
	ds_read_b128 v[186:189], v219 offset:13376
	ds_read_b128 v[178:181], v219 offset:20000
	ds_read_b128 v[182:185], v219 offset:20032
	s_add_i32 s16, s16, 2
	v_cmp_neq_f32_e64 s[0:1], -v220, v191
	s_cmp_eq_u64 s[0:1], 0
	v_sub_f32_e32 v192, 0, v220
	s_cselect_b64 s[48:49], -1, 0
	v_mov_b32_e32 v190, 0
	s_cmp_lg_u64 s[48:49], 0
	s_cbranch_scc1 .Lnegc_keep_0
	v_mov_b32_e32 v129, v192
	v_mov_b32_e32 v128, v192
	v_mov_b32_e32 v127, v192
	v_mov_b32_e32 v126, v192
	v_mov_b32_e32 v125, v192
	v_mov_b32_e32 v124, v192
	v_mov_b32_e32 v123, v192
	v_mov_b32_e32 v122, v192
	v_mov_b32_e32 v121, v192
	v_mov_b32_e32 v120, v192
	v_mov_b32_e32 v119, v192
	v_mov_b32_e32 v118, v192
	v_mov_b32_e32 v117, v192
	v_mov_b32_e32 v116, v192
	v_mov_b32_e32 v115, v192
	v_mov_b32_e32 v114, v192
.Lnegc_keep_0:
	v_max3_f32 v0, v240, v50, v51
	v_max3_f32 v70, v240, v52, v53
	s_nop 0
	v_max3_f32 v0, v0, v34, v35
	v_max3_f32 v70, v70, v36, v37
	s_waitcnt lgkmcnt(5)
	v_mfma_f32_32x32x16_bf16 v[98:113], v[66:69], v[130:133], v[114:129]
	ds_read_b128 v[94:97], v219 offset:13408
	ds_read_b128 v[82:85], v219 offset:20064
	s_min_u32 s4, s16, 29
	s_add_i32 s6, s4, 2
	v_mad_u64_u32 v[196:197], s[0:1], v194, s6, v[206:207]
	global_load_dwordx4 v[162:165], v[196:197], off
	v_mad_u64_u32 v[196:197], s[0:1], v208, s6, v[210:211]
	global_load_dwordx4 v[158:161], v[196:197], off
	global_load_dwordx4 v[154:157], v[214:215], off
	v_max3_f32 v0, v0, v54, v55
	v_max3_f32 v70, v70, v56, v57
	s_nop 0
	v_max3_f32 v0, v0, v38, v39
	v_max3_f32 v70, v70, v40, v41
	s_nop 0
	v_max3_f32 v66, v70, v60, v61
	v_max3_f32 v0, v0, v58, v59
	s_nop 0
	v_max3_f32 v193, v66, v44, v45
	s_waitcnt lgkmcnt(5)
	v_mfma_f32_32x32x16_bf16 v[66:81], v[86:89], v[130:133], v[114:129]
	v_max3_f32 v0, v0, v42, v43
	ds_read_b128 v[90:93], v219 offset:13440
	ds_read_b128 v[86:89], v219 offset:20096
	ds_read_b64_tr_b16 v[170:171], v221 offset:26624
	ds_read_b64_tr_b16 v[172:173], v221 offset:27136
	ds_read_b64_tr_b16 v[166:167], v221 offset:30720
	ds_read_b64_tr_b16 v[168:169], v221 offset:31232
	v_mfma_f32_32x32x16_bf16 v[98:113], v[174:177], v[134:137], v[98:113]
	v_max3_f32 v0, v0, v62, v63
	v_max3_f32 v174, v193, v64, v65
	s_nop 0
	v_max3_f32 v0, v0, v46, v47
	v_max3_f32 v174, v174, v48, v49
	s_waitcnt lgkmcnt(9)
	v_mfma_f32_32x32x16_bf16 v[66:81], v[178:181], v[134:137], v[66:81]
	v_max_f32_e32 v0, v0, v174
	s_nop 0
	v_mov_b32_e32 v174, v0
	s_nop 1
	v_permlane32_swap_b32_e32 v0, v174
	v_max_f32_e32 v0, v0, v174
	s_nop 0
	v_cmp_lt_f32_e32 vcc, s2, v0
	v_cmp_gt_f32_e64 s[0:1], s3, v0
	s_or_b64 vcc, vcc, s[0:1]
	v_cndmask_b32_e64 v174, 0, 1, vcc
	v_cmp_ne_u32_e64 s[50:51], 0, v174
	s_cmp_lg_u64 s[50:51], 0
	s_cselect_b64 s[14:15], -1, 0
	s_cbranch_vccz .LBB0_735
	v_cmp_lt_f32_e32 vcc, 0, v0
	s_or_b64 vcc, vcc, s[0:1]
	s_nop 0
	v_cndmask_b32_e32 v190, 0, v0, vcc
	v_exp_f32_e64 v0, -v190
	v_pk_add_f32 v[50:51], v[50:51], v[190:191] op_sel_hi:[1,0] neg_lo:[0,1] neg_hi:[0,1]
	v_pk_add_f32 v[52:53], v[52:53], v[190:191] op_sel_hi:[1,0] neg_lo:[0,1] neg_hi:[0,1]
	v_pk_add_f32 v[54:55], v[54:55], v[190:191] op_sel_hi:[1,0] neg_lo:[0,1] neg_hi:[0,1]
	v_pk_add_f32 v[56:57], v[56:57], v[190:191] op_sel_hi:[1,0] neg_lo:[0,1] neg_hi:[0,1]
	v_pk_add_f32 v[58:59], v[58:59], v[190:191] op_sel_hi:[1,0] neg_lo:[0,1] neg_hi:[0,1]
	v_pk_add_f32 v[60:61], v[60:61], v[190:191] op_sel_hi:[1,0] neg_lo:[0,1] neg_hi:[0,1]
	v_pk_add_f32 v[62:63], v[62:63], v[190:191] op_sel_hi:[1,0] neg_lo:[0,1] neg_hi:[0,1]
	v_pk_add_f32 v[64:65], v[64:65], v[190:191] op_sel_hi:[1,0] neg_lo:[0,1] neg_hi:[0,1]
	v_sub_f32_e32 v49, v49, v190
	v_sub_f32_e32 v48, v48, v190
	v_sub_f32_e32 v47, v47, v190
	v_sub_f32_e32 v46, v46, v190
	v_sub_f32_e32 v45, v45, v190
	v_sub_f32_e32 v44, v44, v190
	v_sub_f32_e32 v43, v43, v190
	v_sub_f32_e32 v42, v42, v190
	v_sub_f32_e32 v41, v41, v190
	v_sub_f32_e32 v40, v40, v190
	v_sub_f32_e32 v39, v39, v190
	v_sub_f32_e32 v38, v38, v190
	v_sub_f32_e32 v37, v37, v190
	v_sub_f32_e32 v36, v36, v190
	v_sub_f32_e32 v35, v35, v190
	v_sub_f32_e32 v34, v34, v190
	v_add_f32_e32 v220, v220, v190
	s_branch .LBB0_736

.LBB0_744:
	v_cndmask_b32_e64 v83, v192, v191, s[48:49]
	ds_read_b128 v[34:37], v219
	ds_read_b128 v[174:177], v219 offset:32
	ds_read_b128 v[88:91], v219 offset:6656
	ds_read_b128 v[190:193], v219 offset:64
	ds_read_b128 v[178:181], v219 offset:6688
	ds_read_b128 v[186:189], v219 offset:6720
	v_cmp_neq_f32_e64 s[0:1], -v220, v83
	s_cmp_eq_u64 s[0:1], 0
	v_sub_f32_e32 v223, 0, v220
	s_cselect_b64 s[48:49], -1, 0
	v_mov_b32_e32 v216, 0
	s_cmp_lg_u64 s[48:49], 0
	s_cbranch_scc1 .Lnegc_keep_1
	v_mov_b32_e32 v129, v223
	v_mov_b32_e32 v128, v223
	v_mov_b32_e32 v127, v223
	v_mov_b32_e32 v126, v223
	v_mov_b32_e32 v125, v223
	v_mov_b32_e32 v124, v223
	v_mov_b32_e32 v123, v223
	v_mov_b32_e32 v122, v223
	v_mov_b32_e32 v121, v223
	v_mov_b32_e32 v120, v223
	v_mov_b32_e32 v119, v223
	v_mov_b32_e32 v118, v223
	v_mov_b32_e32 v117, v223
	v_mov_b32_e32 v116, v223
	v_mov_b32_e32 v115, v223
	v_mov_b32_e32 v114, v223
.Lnegc_keep_1:
	v_max3_f32 v38, v240, v98, v99
	v_max3_f32 v39, v240, v100, v101
	v_max3_f32 v38, v38, v66, v67
	v_max3_f32 v39, v39, v68, v69
	s_waitcnt lgkmcnt(5)
	v_mfma_f32_32x32x16_bf16 v[50:65], v[34:37], v[130:133], v[114:129]
	ds_read_b128 v[182:185], v219 offset:96
	ds_read_b128 v[84:87], v219 offset:6752
	s_min_u32 s0, s16, 28
	s_add_i32 s6, s0, 3
	v_mad_u64_u32 v[196:197], s[0:1], v194, s6, v[206:207]
	global_load_dwordx4 v[162:165], v[196:197], off
	v_mad_u64_u32 v[196:197], s[0:1], v208, s6, v[210:211]
	s_lshl_b32 s40, s4, 18
	global_load_dwordx4 v[158:161], v[196:197], off
	v_lshl_add_u64 v[196:197], v[212:213], 0, s[40:41]
	s_mov_b32 s0, 0x80000
	v_add_co_u32_e32 v196, vcc, s0, v196
	s_nop 1
	v_addc_co_u32_e32 v197, vcc, 0, v197, vcc
	global_load_dwordx4 v[154:157], v[196:197], off offset:128
	v_max3_f32 v38, v38, v102, v103
	v_max3_f32 v39, v39, v104, v105
	s_nop 0
	v_max3_f32 v38, v38, v70, v71
	v_max3_f32 v39, v39, v72, v73
	s_nop 0
	v_max3_f32 v34, v38, v106, v107
	v_max3_f32 v35, v39, v108, v109
	s_nop 0
	v_max3_f32 v96, v34, v74, v75
	v_max3_f32 v97, v35, v76, v77
	s_waitcnt lgkmcnt(5)
	v_mfma_f32_32x32x16_bf16 v[34:49], v[88:91], v[130:133], v[114:129]
	ds_read_b128 v[92:95], v219 offset:128
	ds_read_b128 v[88:91], v219 offset:6784
	ds_read_b64_tr_b16 v[170:171], v221 offset:34816
	ds_read_b64_tr_b16 v[172:173], v221 offset:35328
	ds_read_b64_tr_b16 v[166:167], v221 offset:38912
	ds_read_b64_tr_b16 v[168:169], v221 offset:39424
	v_mfma_f32_32x32x16_bf16 v[50:65], v[174:177], v[134:137], v[50:65]
	v_max3_f32 v96, v96, v110, v111
	v_max3_f32 v97, v97, v112, v113
	s_nop 0
	v_max3_f32 v96, v96, v78, v79
	v_max3_f32 v97, v97, v80, v81
	s_waitcnt lgkmcnt(9)
	v_mfma_f32_32x32x16_bf16 v[34:49], v[178:181], v[134:137], v[34:49]
	v_max_f32_e32 v96, v96, v97
	s_nop 0
	v_mov_b32_e32 v97, v96
	s_nop 1
	v_permlane32_swap_b32_e32 v96, v97
	v_max_f32_e32 v96, v96, v97
	s_nop 0
	v_cmp_lt_f32_e32 vcc, s2, v96
	v_cmp_gt_f32_e64 s[0:1], s3, v96
	s_or_b64 vcc, vcc, s[0:1]
	v_cndmask_b32_e64 v97, 0, 1, vcc
	v_cmp_ne_u32_e64 s[50:51], 0, v97
	s_cmp_lg_u64 s[50:51], 0
	s_cselect_b64 s[14:15], -1, 0
	s_cbranch_vccz .LBB0_746
	v_cmp_lt_f32_e32 vcc, 0, v96
	s_or_b64 vcc, vcc, s[0:1]
	s_nop 0
	v_cndmask_b32_e32 v216, 0, v96, vcc
	v_exp_f32_e64 v218, -v216
	v_pk_add_f32 v[98:99], v[98:99], v[216:217] op_sel_hi:[1,0] neg_lo:[0,1] neg_hi:[0,1]
	v_pk_add_f32 v[100:101], v[100:101], v[216:217] op_sel_hi:[1,0] neg_lo:[0,1] neg_hi:[0,1]
	v_pk_add_f32 v[102:103], v[102:103], v[216:217] op_sel_hi:[1,0] neg_lo:[0,1] neg_hi:[0,1]
	v_pk_add_f32 v[104:105], v[104:105], v[216:217] op_sel_hi:[1,0] neg_lo:[0,1] neg_hi:[0,1]
	v_pk_add_f32 v[106:107], v[106:107], v[216:217] op_sel_hi:[1,0] neg_lo:[0,1] neg_hi:[0,1]
	v_pk_add_f32 v[108:109], v[108:109], v[216:217] op_sel_hi:[1,0] neg_lo:[0,1] neg_hi:[0,1]
	v_pk_add_f32 v[110:111], v[110:111], v[216:217] op_sel_hi:[1,0] neg_lo:[0,1] neg_hi:[0,1]
	v_pk_add_f32 v[112:113], v[112:113], v[216:217] op_sel_hi:[1,0] neg_lo:[0,1] neg_hi:[0,1]
	v_sub_f32_e32 v81, v81, v216
	v_sub_f32_e32 v80, v80, v216
	v_sub_f32_e32 v79, v79, v216
	v_sub_f32_e32 v78, v78, v216
	v_sub_f32_e32 v77, v77, v216
	v_sub_f32_e32 v76, v76, v216
	v_sub_f32_e32 v75, v75, v216
	v_sub_f32_e32 v74, v74, v216
	v_sub_f32_e32 v73, v73, v216
	v_sub_f32_e32 v72, v72, v216
	v_sub_f32_e32 v71, v71, v216
	v_sub_f32_e32 v70, v70, v216
	v_sub_f32_e32 v69, v69, v216
	v_sub_f32_e32 v68, v68, v216
	v_sub_f32_e32 v67, v67, v216
	v_sub_f32_e32 v66, v66, v216
	v_add_f32_e32 v220, v220, v216
	s_branch .LBB0_747
